# tswait: FFN-in tile switch, second-segment wait of the peeled first iteration relaxed to vmcnt(16) from the second tile on (does not wait for the SwiGLU store acks); on top of xbpre
# speedup vs baseline: 1.0028x; 1.0028x over previous
.LBB0_1001:
	s_ashr_i32 s17, s16, 31
	s_lshl_b64 s[18:19], s[16:17], 19
	s_add_u32 s18, s92, s18
	s_addc_u32 s19, s93, s19
	s_and_b64 s[20:21], s[6:7], exec
	s_cselect_b32 s17, s19, s29
	s_cselect_b32 s51, s18, s28
	s_ashr_i32 s15, s14, 31
	s_lshl_b64 s[20:21], s[14:15], 19
	s_add_u32 s20, s41, s20
	s_addc_u32 s21, s42, s21
	s_and_b64 s[30:31], s[6:7], exec
	s_cselect_b32 s15, s21, s25
	s_cselect_b32 s52, s20, s24
	s_add_u32 s53, s24, 0x100
	s_addc_u32 s61, s25, 0
	s_add_u32 s24, s28, 0x40080
	s_addc_u32 s25, s29, 0
	s_mov_b32 s62, -2
	s_add_u32 s28, s24, 0xfffc0080
	s_addc_u32 s29, s25, -1
	s_add_i32 s63, 0, 0x10000
	s_cmp_eq_u32 s62, 12
	s_cselect_b32 s31, s17, s29
	s_cselect_b32 s30, s51, s28
	v_add_u32_e32 v140, s63, v143
	s_cselect_b32 s29, s15, s61
	s_cselect_b32 s28, s52, s53
	s_add_i32 s72, 0, 0x14000
	ds_read_b128 v[146:149], v140
	ds_read_b128 v[150:153], v140 offset:1024
	ds_read_b128 v[154:157], v140 offset:2048
	ds_read_b128 v[158:161], v140 offset:3072
	v_add_u32_e32 v140, s72, v143
	ds_read_b128 v[162:165], v140
	ds_read_b128 v[166:169], v140 offset:1024
	ds_read_b128 v[170:173], v140 offset:2048
	ds_read_b128 v[174:177], v140 offset:3072
	v_lshl_add_u64 v[140:141], s[24:25], 0, v[138:139]
	s_add_i32 m0, s23, 0xc000
	ds_read_b128 v[178:181], v145
	ds_read_b128 v[182:185], v145 offset:1024
	ds_read_b128 v[186:189], v145 offset:2048
	ds_read_b128 v[190:193], v145 offset:3072
	ds_read_b128 v[194:197], v145 offset:4096
	ds_read_b128 v[198:201], v145 offset:5120
	ds_read_b128 v[202:205], v145 offset:6144
	ds_read_b128 v[206:209], v145 offset:7168
	global_load_lds_dwordx4 v[140:141], off
	v_lshl_add_u64 v[140:141], s[24:25], 0, v[136:137]
	s_add_i32 m0, s23, 0xe000
	s_nop 0
	global_load_lds_dwordx4 v[140:141], off
	s_waitcnt vmcnt(8)
	s_waitcnt lgkmcnt(0)
	s_barrier
	s_setprio 1
	s_waitcnt lgkmcnt(0)
	v_mfma_f32_16x16x32_bf16 v[126:129], v[146:149], v[178:181], 0
	v_mfma_f32_16x16x32_bf16 v[122:125], v[154:157], v[178:181], 0
	v_mfma_f32_16x16x32_bf16 v[110:113], v[146:149], v[186:189], 0
	v_mfma_f32_16x16x32_bf16 v[106:109], v[154:157], v[186:189], 0
	v_mfma_f32_16x16x32_bf16 v[94:97], v[146:149], v[194:197], 0
	v_mfma_f32_16x16x32_bf16 v[90:93], v[154:157], v[194:197], 0
	v_mfma_f32_16x16x32_bf16 v[78:81], v[146:149], v[202:205], 0
	v_mfma_f32_16x16x32_bf16 v[74:77], v[154:157], v[202:205], 0
	v_mfma_f32_16x16x32_bf16 v[126:129], v[150:153], v[182:185], v[126:129]
	v_mfma_f32_16x16x32_bf16 v[122:125], v[158:161], v[182:185], v[122:125]
	v_mfma_f32_16x16x32_bf16 v[110:113], v[150:153], v[190:193], v[110:113]
	v_mfma_f32_16x16x32_bf16 v[106:109], v[158:161], v[190:193], v[106:109]
	v_mfma_f32_16x16x32_bf16 v[94:97], v[150:153], v[198:201], v[94:97]
	v_mfma_f32_16x16x32_bf16 v[90:93], v[158:161], v[198:201], v[90:93]
	v_mfma_f32_16x16x32_bf16 v[78:81], v[150:153], v[206:209], v[78:81]
	v_mfma_f32_16x16x32_bf16 v[74:77], v[158:161], v[206:209], v[74:77]
	s_setprio 0
	s_setprio 1
	v_mfma_f32_16x16x32_bf16 v[118:121], v[162:165], v[178:181], 0
	v_mfma_f32_16x16x32_bf16 v[114:117], v[170:173], v[178:181], 0
	v_mfma_f32_16x16x32_bf16 v[102:105], v[162:165], v[186:189], 0
	v_mfma_f32_16x16x32_bf16 v[98:101], v[170:173], v[186:189], 0
	v_mfma_f32_16x16x32_bf16 v[86:89], v[162:165], v[194:197], 0
	v_mfma_f32_16x16x32_bf16 v[82:85], v[170:173], v[194:197], 0
	v_mfma_f32_16x16x32_bf16 v[70:73], v[162:165], v[202:205], 0
	v_mfma_f32_16x16x32_bf16 v[66:69], v[170:173], v[202:205], 0
	v_mfma_f32_16x16x32_bf16 v[118:121], v[166:169], v[182:185], v[118:121]
	v_mfma_f32_16x16x32_bf16 v[114:117], v[174:177], v[182:185], v[114:117]
	v_mfma_f32_16x16x32_bf16 v[102:105], v[166:169], v[190:193], v[102:105]
	v_mfma_f32_16x16x32_bf16 v[98:101], v[174:177], v[190:193], v[98:101]
	v_mfma_f32_16x16x32_bf16 v[86:89], v[166:169], v[198:201], v[86:89]
	v_mfma_f32_16x16x32_bf16 v[82:85], v[174:177], v[198:201], v[82:85]
	v_mfma_f32_16x16x32_bf16 v[70:73], v[166:169], v[206:209], v[70:73]
	v_mfma_f32_16x16x32_bf16 v[66:69], v[174:177], v[206:209], v[66:69]
	s_setprio 0
	s_barrier
	s_add_i32 s63, s63, s40
	v_lshl_add_u64 v[140:141], s[28:29], 0, v[0:1]
	s_mov_b32 m0, s63
	ds_read_b128 v[178:181], v145 offset:16384
	ds_read_b128 v[182:185], v145 offset:17408
	ds_read_b128 v[186:189], v145 offset:18432
	ds_read_b128 v[190:193], v145 offset:19456
	ds_read_b128 v[194:197], v145 offset:20480
	ds_read_b128 v[198:201], v145 offset:21504
	ds_read_b128 v[202:205], v145 offset:22528
	ds_read_b128 v[206:209], v145 offset:23552
	global_load_lds_dwordx4 v[140:141], off
	s_add_i32 m0, s63, 0x2000
	s_add_u32 s70, s28, 0x40000
	v_lshl_add_u64 v[210:211], s[28:29], 0, v[134:135]
	s_addc_u32 s71, s29, 0
	s_add_i32 s63, s72, s40
	global_load_lds_dwordx4 v[210:211], off
	v_lshl_add_u64 v[212:213], s[70:71], 0, v[0:1]
	s_mov_b32 m0, s63
	v_lshl_add_u64 v[214:215], s[30:31], 0, v[132:133]
	global_load_lds_dwordx4 v[212:213], off
	v_lshl_add_u64 v[212:213], s[70:71], 0, v[134:135]
	s_add_i32 m0, s63, 0x2000
	s_nop 0
	global_load_lds_dwordx4 v[212:213], off
	v_lshl_add_u64 v[212:213], s[30:31], 0, v[130:131]
	s_mov_b32 m0, s23
	s_nop 0
	global_load_lds_dwordx4 v[212:213], off
	s_mov_b32 m0, s43
	s_nop 0
	global_load_lds_dwordx4 v[214:215], off
	s_cmp_eq_u32 s49, 1
	s_cbranch_scc1 .Ltw_first
	s_waitcnt vmcnt(16)
	s_branch .Ltw_join
.Ltw_first:
	s_waitcnt vmcnt(8)
.Ltw_join:
	s_waitcnt lgkmcnt(0)
	s_barrier
	s_setprio 1
	s_waitcnt lgkmcnt(0)
	v_mfma_f32_16x16x32_bf16 v[62:65], v[146:149], v[178:181], 0
	v_mfma_f32_16x16x32_bf16 v[58:61], v[154:157], v[178:181], 0
	v_mfma_f32_16x16x32_bf16 v[46:49], v[146:149], v[186:189], 0
	v_mfma_f32_16x16x32_bf16 v[42:45], v[154:157], v[186:189], 0
	v_mfma_f32_16x16x32_bf16 v[30:33], v[146:149], v[194:197], 0
	v_mfma_f32_16x16x32_bf16 v[26:29], v[154:157], v[194:197], 0
	v_mfma_f32_16x16x32_bf16 v[14:17], v[146:149], v[202:205], 0
	v_mfma_f32_16x16x32_bf16 v[10:13], v[154:157], v[202:205], 0
	v_mfma_f32_16x16x32_bf16 v[62:65], v[150:153], v[182:185], v[62:65]
	v_mfma_f32_16x16x32_bf16 v[58:61], v[158:161], v[182:185], v[58:61]
	v_mfma_f32_16x16x32_bf16 v[46:49], v[150:153], v[190:193], v[46:49]
	v_mfma_f32_16x16x32_bf16 v[42:45], v[158:161], v[190:193], v[42:45]
	v_mfma_f32_16x16x32_bf16 v[30:33], v[150:153], v[198:201], v[30:33]
	v_mfma_f32_16x16x32_bf16 v[26:29], v[158:161], v[198:201], v[26:29]
	v_mfma_f32_16x16x32_bf16 v[14:17], v[150:153], v[206:209], v[14:17]
	v_mfma_f32_16x16x32_bf16 v[10:13], v[158:161], v[206:209], v[10:13]
	s_setprio 0
	s_setprio 1
	v_mfma_f32_16x16x32_bf16 v[54:57], v[162:165], v[178:181], 0
	v_mfma_f32_16x16x32_bf16 v[50:53], v[170:173], v[178:181], 0
	v_mfma_f32_16x16x32_bf16 v[38:41], v[162:165], v[186:189], 0
	v_mfma_f32_16x16x32_bf16 v[34:37], v[170:173], v[186:189], 0
	v_mfma_f32_16x16x32_bf16 v[22:25], v[162:165], v[194:197], 0
	v_mfma_f32_16x16x32_bf16 v[18:21], v[170:173], v[194:197], 0
	v_mfma_f32_16x16x32_bf16 v[6:9], v[162:165], v[202:205], 0
	v_mfma_f32_16x16x32_bf16 v[2:5], v[170:173], v[202:205], 0
	v_mfma_f32_16x16x32_bf16 v[54:57], v[166:169], v[182:185], v[54:57]
	v_mfma_f32_16x16x32_bf16 v[50:53], v[174:177], v[182:185], v[50:53]
	v_mfma_f32_16x16x32_bf16 v[38:41], v[166:169], v[190:193], v[38:41]
	v_mfma_f32_16x16x32_bf16 v[34:37], v[174:177], v[190:193], v[34:37]
	v_mfma_f32_16x16x32_bf16 v[22:25], v[166:169], v[198:201], v[22:25]
	v_mfma_f32_16x16x32_bf16 v[18:21], v[174:177], v[198:201], v[18:21]
	v_mfma_f32_16x16x32_bf16 v[6:9], v[166:169], v[206:209], v[6:9]
	v_mfma_f32_16x16x32_bf16 v[2:5], v[174:177], v[206:209], v[2:5]
	s_setprio 0
	s_barrier
	s_add_i32 s63, 0, 0x18000
	s_add_i32 s70, 0, 0x1c000
	v_add_u32_e32 v158, s63, v143
	v_add_u32_e32 v174, s70, v143
	ds_read_b128 v[146:149], v158
	ds_read_b128 v[150:153], v158 offset:1024
	ds_read_b128 v[154:157], v158 offset:2048
	ds_read_b128 v[158:161], v158 offset:3072
	ds_read_b128 v[162:165], v174
	ds_read_b128 v[166:169], v174 offset:1024
	ds_read_b128 v[170:173], v174 offset:2048
	ds_read_b128 v[174:177], v174 offset:3072
	s_add_u32 s30, s30, 0x40000
	s_addc_u32 s31, s31, 0
	s_mov_b32 m0, s44
	v_lshl_add_u64 v[216:217], s[30:31], 0, v[130:131]
	ds_read_b128 v[178:181], v145 offset:32768
	ds_read_b128 v[182:185], v145 offset:33792
	ds_read_b128 v[186:189], v145 offset:34816
	ds_read_b128 v[190:193], v145 offset:35840
	ds_read_b128 v[194:197], v145 offset:36864
	ds_read_b128 v[198:201], v145 offset:37888
	ds_read_b128 v[202:205], v145 offset:38912
	ds_read_b128 v[206:209], v145 offset:39936
	global_load_lds_dwordx4 v[216:217], off
	v_lshl_add_u64 v[216:217], s[30:31], 0, v[132:133]
	s_mov_b32 m0, s45
	s_nop 0
	global_load_lds_dwordx4 v[216:217], off
	s_waitcnt vmcnt(8)
	s_waitcnt lgkmcnt(0)
	s_barrier
	s_setprio 1
	s_waitcnt lgkmcnt(0)
	v_mfma_f32_16x16x32_bf16 v[126:129], v[146:149], v[178:181], v[126:129]
	v_mfma_f32_16x16x32_bf16 v[122:125], v[154:157], v[178:181], v[122:125]
	v_mfma_f32_16x16x32_bf16 v[110:113], v[146:149], v[186:189], v[110:113]
	v_mfma_f32_16x16x32_bf16 v[106:109], v[154:157], v[186:189], v[106:109]
	v_mfma_f32_16x16x32_bf16 v[94:97], v[146:149], v[194:197], v[94:97]
	v_mfma_f32_16x16x32_bf16 v[90:93], v[154:157], v[194:197], v[90:93]
	v_mfma_f32_16x16x32_bf16 v[78:81], v[146:149], v[202:205], v[78:81]
	v_mfma_f32_16x16x32_bf16 v[74:77], v[154:157], v[202:205], v[74:77]
	v_mfma_f32_16x16x32_bf16 v[126:129], v[150:153], v[182:185], v[126:129]
	v_mfma_f32_16x16x32_bf16 v[122:125], v[158:161], v[182:185], v[122:125]
	v_mfma_f32_16x16x32_bf16 v[110:113], v[150:153], v[190:193], v[110:113]
	v_mfma_f32_16x16x32_bf16 v[106:109], v[158:161], v[190:193], v[106:109]
	v_mfma_f32_16x16x32_bf16 v[94:97], v[150:153], v[198:201], v[94:97]
	v_mfma_f32_16x16x32_bf16 v[90:93], v[158:161], v[198:201], v[90:93]
	v_mfma_f32_16x16x32_bf16 v[78:81], v[150:153], v[206:209], v[78:81]
	v_mfma_f32_16x16x32_bf16 v[74:77], v[158:161], v[206:209], v[74:77]
	s_setprio 0
	s_setprio 1
	v_mfma_f32_16x16x32_bf16 v[118:121], v[162:165], v[178:181], v[118:121]
	v_mfma_f32_16x16x32_bf16 v[114:117], v[170:173], v[178:181], v[114:117]
	v_mfma_f32_16x16x32_bf16 v[102:105], v[162:165], v[186:189], v[102:105]
	v_mfma_f32_16x16x32_bf16 v[98:101], v[170:173], v[186:189], v[98:101]
	v_mfma_f32_16x16x32_bf16 v[86:89], v[162:165], v[194:197], v[86:89]
	v_mfma_f32_16x16x32_bf16 v[82:85], v[170:173], v[194:197], v[82:85]
	v_mfma_f32_16x16x32_bf16 v[70:73], v[162:165], v[202:205], v[70:73]
	v_mfma_f32_16x16x32_bf16 v[66:69], v[170:173], v[202:205], v[66:69]
	v_mfma_f32_16x16x32_bf16 v[118:121], v[166:169], v[182:185], v[118:121]
	v_mfma_f32_16x16x32_bf16 v[114:117], v[174:177], v[182:185], v[114:117]
	v_mfma_f32_16x16x32_bf16 v[102:105], v[166:169], v[190:193], v[102:105]
	v_mfma_f32_16x16x32_bf16 v[98:101], v[174:177], v[190:193], v[98:101]
	v_mfma_f32_16x16x32_bf16 v[86:89], v[166:169], v[198:201], v[86:89]
	v_mfma_f32_16x16x32_bf16 v[82:85], v[174:177], v[198:201], v[82:85]
	v_mfma_f32_16x16x32_bf16 v[70:73], v[166:169], v[206:209], v[70:73]
	v_mfma_f32_16x16x32_bf16 v[66:69], v[174:177], v[206:209], v[66:69]
	s_setprio 0
	s_barrier
	s_add_i32 s30, s63, s40
	v_lshl_add_u64 v[140:141], v[140:141], 0, s[76:77]
	s_mov_b32 m0, s30
	ds_read_b128 v[178:181], v145 offset:49152
	ds_read_b128 v[182:185], v145 offset:50176
	ds_read_b128 v[186:189], v145 offset:51200
	ds_read_b128 v[190:193], v145 offset:52224
	ds_read_b128 v[194:197], v145 offset:53248
	ds_read_b128 v[198:201], v145 offset:54272
	ds_read_b128 v[202:205], v145 offset:55296
	ds_read_b128 v[206:209], v145 offset:56320
	global_load_lds_dwordx4 v[140:141], off
	s_add_i32 m0, s30, 0x2000
	s_add_u32 s28, s28, 0x40080
	v_lshl_add_u64 v[140:141], v[210:211], 0, s[76:77]
	s_addc_u32 s29, s29, 0
	s_add_i32 s30, s70, s40
	global_load_lds_dwordx4 v[140:141], off
	v_lshl_add_u64 v[140:141], s[28:29], 0, v[0:1]
	s_mov_b32 m0, s30
	s_nop 0
	global_load_lds_dwordx4 v[140:141], off
	v_lshl_add_u64 v[140:141], s[28:29], 0, v[134:135]
	s_add_i32 m0, s30, 0x2000
	s_nop 0
	global_load_lds_dwordx4 v[140:141], off
	v_lshl_add_u64 v[140:141], v[212:213], 0, s[76:77]
	s_mov_b32 m0, s46
	s_nop 0
	global_load_lds_dwordx4 v[140:141], off
	v_lshl_add_u64 v[140:141], v[214:215], 0, s[76:77]
	s_mov_b32 m0, s47
	s_nop 0
	global_load_lds_dwordx4 v[140:141], off
	s_waitcnt vmcnt(8)
	s_waitcnt lgkmcnt(0)
	s_barrier
	s_setprio 1
	s_waitcnt lgkmcnt(0)
	v_mfma_f32_16x16x32_bf16 v[62:65], v[146:149], v[178:181], v[62:65]
	v_mfma_f32_16x16x32_bf16 v[58:61], v[154:157], v[178:181], v[58:61]
	v_mfma_f32_16x16x32_bf16 v[46:49], v[146:149], v[186:189], v[46:49]
	v_mfma_f32_16x16x32_bf16 v[42:45], v[154:157], v[186:189], v[42:45]
	v_mfma_f32_16x16x32_bf16 v[30:33], v[146:149], v[194:197], v[30:33]
	v_mfma_f32_16x16x32_bf16 v[26:29], v[154:157], v[194:197], v[26:29]
	v_mfma_f32_16x16x32_bf16 v[14:17], v[146:149], v[202:205], v[14:17]
	v_mfma_f32_16x16x32_bf16 v[10:13], v[154:157], v[202:205], v[10:13]
	v_mfma_f32_16x16x32_bf16 v[62:65], v[150:153], v[182:185], v[62:65]
	v_mfma_f32_16x16x32_bf16 v[58:61], v[158:161], v[182:185], v[58:61]
	v_mfma_f32_16x16x32_bf16 v[46:49], v[150:153], v[190:193], v[46:49]
	v_mfma_f32_16x16x32_bf16 v[42:45], v[158:161], v[190:193], v[42:45]
	v_mfma_f32_16x16x32_bf16 v[30:33], v[150:153], v[198:201], v[30:33]
	v_mfma_f32_16x16x32_bf16 v[26:29], v[158:161], v[198:201], v[26:29]
	v_mfma_f32_16x16x32_bf16 v[14:17], v[150:153], v[206:209], v[14:17]
	v_mfma_f32_16x16x32_bf16 v[10:13], v[158:161], v[206:209], v[10:13]
	s_setprio 0
	s_setprio 1
	v_mfma_f32_16x16x32_bf16 v[54:57], v[162:165], v[178:181], v[54:57]
	v_mfma_f32_16x16x32_bf16 v[50:53], v[170:173], v[178:181], v[50:53]
	v_mfma_f32_16x16x32_bf16 v[38:41], v[162:165], v[186:189], v[38:41]
	v_mfma_f32_16x16x32_bf16 v[34:37], v[170:173], v[186:189], v[34:37]
	v_mfma_f32_16x16x32_bf16 v[22:25], v[162:165], v[194:197], v[22:25]
	v_mfma_f32_16x16x32_bf16 v[18:21], v[170:173], v[194:197], v[18:21]
	v_mfma_f32_16x16x32_bf16 v[6:9], v[162:165], v[202:205], v[6:9]
	v_mfma_f32_16x16x32_bf16 v[2:5], v[170:173], v[202:205], v[2:5]
	v_mfma_f32_16x16x32_bf16 v[54:57], v[166:169], v[182:185], v[54:57]
	v_mfma_f32_16x16x32_bf16 v[50:53], v[174:177], v[182:185], v[50:53]
	v_mfma_f32_16x16x32_bf16 v[38:41], v[166:169], v[190:193], v[38:41]
	v_mfma_f32_16x16x32_bf16 v[34:37], v[174:177], v[190:193], v[34:37]
	v_mfma_f32_16x16x32_bf16 v[22:25], v[166:169], v[198:201], v[22:25]
	v_mfma_f32_16x16x32_bf16 v[18:21], v[174:177], v[198:201], v[18:21]
	v_mfma_f32_16x16x32_bf16 v[6:9], v[166:169], v[206:209], v[6:9]
	v_mfma_f32_16x16x32_bf16 v[2:5], v[174:177], v[206:209], v[2:5]
	s_setprio 0
	s_barrier
	s_add_i32 s62, s62, 2
	s_add_u32 s53, s53, 0x100
	s_addc_u32 s61, s61, 0
	s_add_u32 s24, s24, 0x100
	s_addc_u32 s25, s25, 0
	s_cmp_gt_u32 s62, 13
